# neighbourhood attention: rel-pos bias of the first key half loaded unconditionally (16 loads in flight + select) instead of 16 exec-masked branch/load/wait round trips
# speedup vs baseline: 1.0111x; 1.0111x over previous
; __device__ __forceinline__ int crow(int r, int h) { return (r & 3) + 8 * (r >> 2) + 4 * h; }
;     ...
;             const bool biased = BIAS && t < nlat;
;             if (biased) {
;                 const int drow = (kr0 + t - qr + 7) * 32;
;                 int qcl = qc, csl = cs; asm volatile("" : "+v"(qcl), "+v"(csl));
; #pragma unroll
;                 for (int r = 0; r < 16; ++r) {
;                     const int k0 = crow(r, h2), k1 = k0 + 32;
.LBB0_476:
	s_andn2_b64 vcc, exec, s[2:3]
	s_mov_b64 s[48:49], 0
	s_cbranch_vccnz .LBB0_510
	v_mov_b32_e32 v114, v192
	v_mov_b32_e32 v176, v193
	s_add_i32 s4, s70, s71

; __device__ __forceinline__ int crow(int r, int h) { return (r & 3) + 8 * (r >> 2) + 4 * h; }
;     ...
;                     const int k0 = crow(r, h2), k1 = k0 + 32;
;                     int d0 = k0 - qcl + 15, d1 = k1 - qcl + 15; d0 = d0 < 0 ? 0 : (d0 > 30 ? 30 : d0); d1 = d1 < 0 ? 0 : (d1 > 30 ? 30 : d1);
;                     const float b0 = rpbL[drow + d0], b1 = rpbL[drow + d1];
	v_sub_u32_e32 v166, v188, v114
	v_med3_i32 v166, v166, -15, 15
	v_lshl_add_u32 v166, v166, 2, s4
	ds_read_b32 v106, v166 offset:44988

; __device__ __forceinline__ int crow(int r, int h) { return (r & 3) + 8 * (r >> 2) + 4 * h; }
;     ...
;                     const int k0 = crow(r, h2), k1 = k0 + 32;
;                     int d0 = k0 - qcl + 15, d1 = k1 - qcl + 15; d0 = d0 < 0 ? 0 : (d0 > 30 ? 30 : d0); d1 = d1 < 0 ? 0 : (d1 > 30 ? 30 : d1);
;                     const float b0 = rpbL[drow + d0], b1 = rpbL[drow + d1];
	v_sub_u32_e32 v166, v212, v114
	v_med3_i32 v166, v166, -15, 15
	v_lshl_add_u32 v166, v166, 2, s4
	ds_read_b32 v107, v166 offset:44988

; __device__ __forceinline__ int crow(int r, int h) { return (r & 3) + 8 * (r >> 2) + 4 * h; }
;     ...
;                     const int k0 = crow(r, h2), k1 = k0 + 32;
;                     int d0 = k0 - qcl + 15, d1 = k1 - qcl + 15; d0 = d0 < 0 ? 0 : (d0 > 30 ? 30 : d0); d1 = d1 < 0 ? 0 : (d1 > 30 ? 30 : d1);
;                     const float b0 = rpbL[drow + d0], b1 = rpbL[drow + d1];
	v_sub_u32_e32 v166, v214, v114
	v_med3_i32 v166, v166, -15, 15
	v_lshl_add_u32 v166, v166, 2, s4
	ds_read_b32 v108, v166 offset:44988

; __device__ __forceinline__ int crow(int r, int h) { return (r & 3) + 8 * (r >> 2) + 4 * h; }
;     ...
;                     const int k0 = crow(r, h2), k1 = k0 + 32;
;                     int d0 = k0 - qcl + 15, d1 = k1 - qcl + 15; d0 = d0 < 0 ? 0 : (d0 > 30 ? 30 : d0); d1 = d1 < 0 ? 0 : (d1 > 30 ? 30 : d1);
;                     const float b0 = rpbL[drow + d0], b1 = rpbL[drow + d1];
	v_sub_u32_e32 v166, v216, v114
	v_med3_i32 v166, v166, -15, 15
	v_lshl_add_u32 v166, v166, 2, s4
	ds_read_b32 v109, v166 offset:44988

; __device__ __forceinline__ int crow(int r, int h) { return (r & 3) + 8 * (r >> 2) + 4 * h; }
;     ...
;                     const int k0 = crow(r, h2), k1 = k0 + 32;
;                     int d0 = k0 - qcl + 15, d1 = k1 - qcl + 15; d0 = d0 < 0 ? 0 : (d0 > 30 ? 30 : d0); d1 = d1 < 0 ? 0 : (d1 > 30 ? 30 : d1);
;                     const float b0 = rpbL[drow + d0], b1 = rpbL[drow + d1];
	v_sub_u32_e32 v166, v218, v114
	v_med3_i32 v166, v166, -15, 15
	v_lshl_add_u32 v166, v166, 2, s4
	ds_read_b32 v110, v166 offset:44988

; __device__ __forceinline__ int crow(int r, int h) { return (r & 3) + 8 * (r >> 2) + 4 * h; }
;     ...
;                     const int k0 = crow(r, h2), k1 = k0 + 32;
;                     int d0 = k0 - qcl + 15, d1 = k1 - qcl + 15; d0 = d0 < 0 ? 0 : (d0 > 30 ? 30 : d0); d1 = d1 < 0 ? 0 : (d1 > 30 ? 30 : d1);
;                     const float b0 = rpbL[drow + d0], b1 = rpbL[drow + d1];
	v_sub_u32_e32 v166, v220, v114
	v_med3_i32 v166, v166, -15, 15
	v_lshl_add_u32 v166, v166, 2, s4
	ds_read_b32 v111, v166 offset:44988

; __device__ __forceinline__ int crow(int r, int h) { return (r & 3) + 8 * (r >> 2) + 4 * h; }
;     ...
;                     const int k0 = crow(r, h2), k1 = k0 + 32;
;                     int d0 = k0 - qcl + 15, d1 = k1 - qcl + 15; d0 = d0 < 0 ? 0 : (d0 > 30 ? 30 : d0); d1 = d1 < 0 ? 0 : (d1 > 30 ? 30 : d1);
;                     const float b0 = rpbL[drow + d0], b1 = rpbL[drow + d1];
	v_sub_u32_e32 v166, v222, v114
	v_med3_i32 v166, v166, -15, 15
	v_lshl_add_u32 v166, v166, 2, s4
	ds_read_b32 v112, v166 offset:44988

; __device__ __forceinline__ int crow(int r, int h) { return (r & 3) + 8 * (r >> 2) + 4 * h; }
;     ...
;                     const int k0 = crow(r, h2), k1 = k0 + 32;
;                     int d0 = k0 - qcl + 15, d1 = k1 - qcl + 15; d0 = d0 < 0 ? 0 : (d0 > 30 ? 30 : d0); d1 = d1 < 0 ? 0 : (d1 > 30 ? 30 : d1);
;                     const float b0 = rpbL[drow + d0], b1 = rpbL[drow + d1];
	v_sub_u32_e32 v166, v224, v114
	v_med3_i32 v166, v166, -15, 15
	v_lshl_add_u32 v166, v166, 2, s4
	ds_read_b32 v113, v166 offset:44988

; __device__ __forceinline__ int crow(int r, int h) { return (r & 3) + 8 * (r >> 2) + 4 * h; }
;     ...
;                     const int k0 = crow(r, h2), k1 = k0 + 32;
;                     int d0 = k0 - qcl + 15, d1 = k1 - qcl + 15; d0 = d0 < 0 ? 0 : (d0 > 30 ? 30 : d0); d1 = d1 < 0 ? 0 : (d1 > 30 ? 30 : d1);
;                     const float b0 = rpbL[drow + d0], b1 = rpbL[drow + d1];
	v_sub_u32_e32 v166, v226, v114
	v_med3_i32 v166, v166, -15, 15
	v_lshl_add_u32 v166, v166, 2, s4
	ds_read_b32 v116, v166 offset:44988

; __device__ __forceinline__ int crow(int r, int h) { return (r & 3) + 8 * (r >> 2) + 4 * h; }
;     ...
;                     const int k0 = crow(r, h2), k1 = k0 + 32;
;                     int d0 = k0 - qcl + 15, d1 = k1 - qcl + 15; d0 = d0 < 0 ? 0 : (d0 > 30 ? 30 : d0); d1 = d1 < 0 ? 0 : (d1 > 30 ? 30 : d1);
;                     const float b0 = rpbL[drow + d0], b1 = rpbL[drow + d1];
	v_sub_u32_e32 v166, v228, v114
	v_med3_i32 v166, v166, -15, 15
	v_lshl_add_u32 v166, v166, 2, s4
	ds_read_b32 v118, v166 offset:44988

; __device__ __forceinline__ int crow(int r, int h) { return (r & 3) + 8 * (r >> 2) + 4 * h; }
;     ...
;                     const int k0 = crow(r, h2), k1 = k0 + 32;
;                     int d0 = k0 - qcl + 15, d1 = k1 - qcl + 15; d0 = d0 < 0 ? 0 : (d0 > 30 ? 30 : d0); d1 = d1 < 0 ? 0 : (d1 > 30 ? 30 : d1);
;                     const float b0 = rpbL[drow + d0], b1 = rpbL[drow + d1];
	v_sub_u32_e32 v166, v230, v114
	v_med3_i32 v166, v166, -15, 15
	v_lshl_add_u32 v166, v166, 2, s4
	ds_read_b32 v120, v166 offset:44988

; __device__ __forceinline__ int crow(int r, int h) { return (r & 3) + 8 * (r >> 2) + 4 * h; }
;     ...
;                     const int k0 = crow(r, h2), k1 = k0 + 32;
;                     int d0 = k0 - qcl + 15, d1 = k1 - qcl + 15; d0 = d0 < 0 ? 0 : (d0 > 30 ? 30 : d0); d1 = d1 < 0 ? 0 : (d1 > 30 ? 30 : d1);
;                     const float b0 = rpbL[drow + d0], b1 = rpbL[drow + d1];
	v_sub_u32_e32 v166, v232, v114
	v_med3_i32 v166, v166, -15, 15
	v_lshl_add_u32 v166, v166, 2, s4
	ds_read_b32 v122, v166 offset:44988

; __device__ __forceinline__ int crow(int r, int h) { return (r & 3) + 8 * (r >> 2) + 4 * h; }
;     ...
;                     const int k0 = crow(r, h2), k1 = k0 + 32;
;                     int d0 = k0 - qcl + 15, d1 = k1 - qcl + 15; d0 = d0 < 0 ? 0 : (d0 > 30 ? 30 : d0); d1 = d1 < 0 ? 0 : (d1 > 30 ? 30 : d1);
;                     const float b0 = rpbL[drow + d0], b1 = rpbL[drow + d1];
	v_sub_u32_e32 v166, v234, v114
	v_med3_i32 v166, v166, -15, 15
	v_lshl_add_u32 v166, v166, 2, s4
	ds_read_b32 v124, v166 offset:44988

; __device__ __forceinline__ int crow(int r, int h) { return (r & 3) + 8 * (r >> 2) + 4 * h; }
;     ...
;                     const int k0 = crow(r, h2), k1 = k0 + 32;
;                     int d0 = k0 - qcl + 15, d1 = k1 - qcl + 15; d0 = d0 < 0 ? 0 : (d0 > 30 ? 30 : d0); d1 = d1 < 0 ? 0 : (d1 > 30 ? 30 : d1);
;                     const float b0 = rpbL[drow + d0], b1 = rpbL[drow + d1];
	v_sub_u32_e32 v166, v236, v114
	v_med3_i32 v166, v166, -15, 15
	v_lshl_add_u32 v166, v166, 2, s4
	ds_read_b32 v126, v166 offset:44988

; __device__ __forceinline__ int crow(int r, int h) { return (r & 3) + 8 * (r >> 2) + 4 * h; }
;     ...
;                     const int k0 = crow(r, h2), k1 = k0 + 32;
;                     int d0 = k0 - qcl + 15, d1 = k1 - qcl + 15; d0 = d0 < 0 ? 0 : (d0 > 30 ? 30 : d0); d1 = d1 < 0 ? 0 : (d1 > 30 ? 30 : d1);
;                     const float b0 = rpbL[drow + d0], b1 = rpbL[drow + d1];
	v_sub_u32_e32 v166, v238, v114
	v_med3_i32 v166, v166, -15, 15
	v_lshl_add_u32 v166, v166, 2, s4
	ds_read_b32 v128, v166 offset:44988

; __device__ __forceinline__ int crow(int r, int h) { return (r & 3) + 8 * (r >> 2) + 4 * h; }
;     ...
;                     const int k0 = crow(r, h2), k1 = k0 + 32;
;                     int d0 = k0 - qcl + 15, d1 = k1 - qcl + 15; d0 = d0 < 0 ? 0 : (d0 > 30 ? 30 : d0); d1 = d1 < 0 ? 0 : (d1 > 30 ? 30 : d1);
;                     const float b0 = rpbL[drow + d0], b1 = rpbL[drow + d1];
	v_sub_u32_e32 v166, v240, v114
	v_med3_i32 v166, v166, -15, 15
	v_lshl_add_u32 v166, v166, 2, s4
	ds_read_b32 v164, v166 offset:44988

; __device__ __forceinline__ int crow(int r, int h) { return (r & 3) + 8 * (r >> 2) + 4 * h; }
;     ...
;                     const int k0 = crow(r, h2), k1 = k0 + 32;
;                     int d0 = k0 - qcl + 15, d1 = k1 - qcl + 15; d0 = d0 < 0 ? 0 : (d0 > 30 ? 30 : d0); d1 = d1 < 0 ? 0 : (d1 > 30 ? 30 : d1);
;                     const float b0 = rpbL[drow + d0], b1 = rpbL[drow + d1];
;                     s0[r] = ((unsigned)(k0 - csl) < 16u) ? s0[r] * C2S + b0 * LOG2E : -1e30f;
;                     s1[r] = ((unsigned)(k1 - csl) < 16u) ? s1[r] * C2S + b1 * LOG2E : -1e30f;
	s_waitcnt lgkmcnt(0)
	v_sub_u32_e32 v168, v188, v176
	v_cmp_gt_u32_e32 vcc, 16, v168
	v_mul_f32_e32 v98, s20, v48
	v_mul_f32_e32 v106, s21, v106
	v_add_f32_e32 v98, v98, v106
	v_cndmask_b32_e32 v98, v202, v98, vcc

; __device__ __forceinline__ int crow(int r, int h) { return (r & 3) + 8 * (r >> 2) + 4 * h; }
;     ...
;                     const int k0 = crow(r, h2), k1 = k0 + 32;
;                     int d0 = k0 - qcl + 15, d1 = k1 - qcl + 15; d0 = d0 < 0 ? 0 : (d0 > 30 ? 30 : d0); d1 = d1 < 0 ? 0 : (d1 > 30 ? 30 : d1);
;                     const float b0 = rpbL[drow + d0], b1 = rpbL[drow + d1];
;                     s0[r] = ((unsigned)(k0 - csl) < 16u) ? s0[r] * C2S + b0 * LOG2E : -1e30f;
;                     s1[r] = ((unsigned)(k1 - csl) < 16u) ? s1[r] * C2S + b1 * LOG2E : -1e30f;
	v_sub_u32_e32 v168, v212, v176
	v_cmp_gt_u32_e32 vcc, 16, v168
	v_mul_f32_e32 v99, s20, v49
	v_mul_f32_e32 v107, s21, v107
	v_add_f32_e32 v99, v99, v107
	v_cndmask_b32_e32 v99, v202, v99, vcc

; __device__ __forceinline__ int crow(int r, int h) { return (r & 3) + 8 * (r >> 2) + 4 * h; }
;     ...
;                     const int k0 = crow(r, h2), k1 = k0 + 32;
;                     int d0 = k0 - qcl + 15, d1 = k1 - qcl + 15; d0 = d0 < 0 ? 0 : (d0 > 30 ? 30 : d0); d1 = d1 < 0 ? 0 : (d1 > 30 ? 30 : d1);
;                     const float b0 = rpbL[drow + d0], b1 = rpbL[drow + d1];
;                     s0[r] = ((unsigned)(k0 - csl) < 16u) ? s0[r] * C2S + b0 * LOG2E : -1e30f;
;                     s1[r] = ((unsigned)(k1 - csl) < 16u) ? s1[r] * C2S + b1 * LOG2E : -1e30f;
	v_sub_u32_e32 v168, v214, v176
	v_cmp_gt_u32_e32 vcc, 16, v168
	v_mul_f32_e32 v100, s20, v50
	v_mul_f32_e32 v108, s21, v108
	v_add_f32_e32 v100, v100, v108
	v_cndmask_b32_e32 v100, v202, v100, vcc

; __device__ __forceinline__ int crow(int r, int h) { return (r & 3) + 8 * (r >> 2) + 4 * h; }
;     ...
;                     const int k0 = crow(r, h2), k1 = k0 + 32;
;                     int d0 = k0 - qcl + 15, d1 = k1 - qcl + 15; d0 = d0 < 0 ? 0 : (d0 > 30 ? 30 : d0); d1 = d1 < 0 ? 0 : (d1 > 30 ? 30 : d1);
;                     const float b0 = rpbL[drow + d0], b1 = rpbL[drow + d1];
;                     s0[r] = ((unsigned)(k0 - csl) < 16u) ? s0[r] * C2S + b0 * LOG2E : -1e30f;
;                     s1[r] = ((unsigned)(k1 - csl) < 16u) ? s1[r] * C2S + b1 * LOG2E : -1e30f;
	v_sub_u32_e32 v168, v216, v176
	v_cmp_gt_u32_e32 vcc, 16, v168
	v_mul_f32_e32 v101, s20, v51
	v_mul_f32_e32 v109, s21, v109
	v_add_f32_e32 v101, v101, v109
	v_cndmask_b32_e32 v101, v202, v101, vcc

; __device__ __forceinline__ int crow(int r, int h) { return (r & 3) + 8 * (r >> 2) + 4 * h; }
;     ...
;                     const int k0 = crow(r, h2), k1 = k0 + 32;
;                     int d0 = k0 - qcl + 15, d1 = k1 - qcl + 15; d0 = d0 < 0 ? 0 : (d0 > 30 ? 30 : d0); d1 = d1 < 0 ? 0 : (d1 > 30 ? 30 : d1);
;                     const float b0 = rpbL[drow + d0], b1 = rpbL[drow + d1];
;                     s0[r] = ((unsigned)(k0 - csl) < 16u) ? s0[r] * C2S + b0 * LOG2E : -1e30f;
;                     s1[r] = ((unsigned)(k1 - csl) < 16u) ? s1[r] * C2S + b1 * LOG2E : -1e30f;
	v_sub_u32_e32 v168, v218, v176
	v_cmp_gt_u32_e32 vcc, 16, v168
	v_mul_f32_e32 v102, s20, v52
	v_mul_f32_e32 v110, s21, v110
	v_add_f32_e32 v102, v102, v110
	v_cndmask_b32_e32 v102, v202, v102, vcc

; __device__ __forceinline__ int crow(int r, int h) { return (r & 3) + 8 * (r >> 2) + 4 * h; }
;     ...
;                     const int k0 = crow(r, h2), k1 = k0 + 32;
;                     int d0 = k0 - qcl + 15, d1 = k1 - qcl + 15; d0 = d0 < 0 ? 0 : (d0 > 30 ? 30 : d0); d1 = d1 < 0 ? 0 : (d1 > 30 ? 30 : d1);
;                     const float b0 = rpbL[drow + d0], b1 = rpbL[drow + d1];
;                     s0[r] = ((unsigned)(k0 - csl) < 16u) ? s0[r] * C2S + b0 * LOG2E : -1e30f;
;                     s1[r] = ((unsigned)(k1 - csl) < 16u) ? s1[r] * C2S + b1 * LOG2E : -1e30f;
	v_sub_u32_e32 v168, v220, v176
	v_cmp_gt_u32_e32 vcc, 16, v168
	v_mul_f32_e32 v103, s20, v53
	v_mul_f32_e32 v111, s21, v111
	v_add_f32_e32 v103, v103, v111
	v_cndmask_b32_e32 v103, v202, v103, vcc

; __device__ __forceinline__ int crow(int r, int h) { return (r & 3) + 8 * (r >> 2) + 4 * h; }
;     ...
;                     const int k0 = crow(r, h2), k1 = k0 + 32;
;                     int d0 = k0 - qcl + 15, d1 = k1 - qcl + 15; d0 = d0 < 0 ? 0 : (d0 > 30 ? 30 : d0); d1 = d1 < 0 ? 0 : (d1 > 30 ? 30 : d1);
;                     const float b0 = rpbL[drow + d0], b1 = rpbL[drow + d1];
;                     s0[r] = ((unsigned)(k0 - csl) < 16u) ? s0[r] * C2S + b0 * LOG2E : -1e30f;
;                     s1[r] = ((unsigned)(k1 - csl) < 16u) ? s1[r] * C2S + b1 * LOG2E : -1e30f;
	v_sub_u32_e32 v168, v222, v176
	v_cmp_gt_u32_e32 vcc, 16, v168
	v_mul_f32_e32 v104, s20, v54
	v_mul_f32_e32 v112, s21, v112
	v_add_f32_e32 v104, v104, v112
	v_cndmask_b32_e32 v104, v202, v104, vcc

; __device__ __forceinline__ int crow(int r, int h) { return (r & 3) + 8 * (r >> 2) + 4 * h; }
;     ...
;                     const int k0 = crow(r, h2), k1 = k0 + 32;
;                     int d0 = k0 - qcl + 15, d1 = k1 - qcl + 15; d0 = d0 < 0 ? 0 : (d0 > 30 ? 30 : d0); d1 = d1 < 0 ? 0 : (d1 > 30 ? 30 : d1);
;                     const float b0 = rpbL[drow + d0], b1 = rpbL[drow + d1];
;                     s0[r] = ((unsigned)(k0 - csl) < 16u) ? s0[r] * C2S + b0 * LOG2E : -1e30f;
;                     s1[r] = ((unsigned)(k1 - csl) < 16u) ? s1[r] * C2S + b1 * LOG2E : -1e30f;
	v_sub_u32_e32 v168, v224, v176
	v_cmp_gt_u32_e32 vcc, 16, v168
	v_mul_f32_e32 v105, s20, v55
	v_mul_f32_e32 v113, s21, v113
	v_add_f32_e32 v105, v105, v113
	v_cndmask_b32_e32 v105, v202, v105, vcc

; __device__ __forceinline__ int crow(int r, int h) { return (r & 3) + 8 * (r >> 2) + 4 * h; }
;     ...
;                     const int k0 = crow(r, h2), k1 = k0 + 32;
;                     int d0 = k0 - qcl + 15, d1 = k1 - qcl + 15; d0 = d0 < 0 ? 0 : (d0 > 30 ? 30 : d0); d1 = d1 < 0 ? 0 : (d1 > 30 ? 30 : d1);
;                     const float b0 = rpbL[drow + d0], b1 = rpbL[drow + d1];
;                     s0[r] = ((unsigned)(k0 - csl) < 16u) ? s0[r] * C2S + b0 * LOG2E : -1e30f;
;                     s1[r] = ((unsigned)(k1 - csl) < 16u) ? s1[r] * C2S + b1 * LOG2E : -1e30f;
	v_sub_u32_e32 v168, v226, v176
	v_cmp_gt_u32_e32 vcc, 16, v168
	v_mul_f32_e32 v106, s20, v56
	v_mul_f32_e32 v116, s21, v116
	v_add_f32_e32 v106, v106, v116
	v_cndmask_b32_e32 v106, v202, v106, vcc

; __device__ __forceinline__ int crow(int r, int h) { return (r & 3) + 8 * (r >> 2) + 4 * h; }
;     ...
;                     const int k0 = crow(r, h2), k1 = k0 + 32;
;                     int d0 = k0 - qcl + 15, d1 = k1 - qcl + 15; d0 = d0 < 0 ? 0 : (d0 > 30 ? 30 : d0); d1 = d1 < 0 ? 0 : (d1 > 30 ? 30 : d1);
;                     const float b0 = rpbL[drow + d0], b1 = rpbL[drow + d1];
;                     s0[r] = ((unsigned)(k0 - csl) < 16u) ? s0[r] * C2S + b0 * LOG2E : -1e30f;
;                     s1[r] = ((unsigned)(k1 - csl) < 16u) ? s1[r] * C2S + b1 * LOG2E : -1e30f;
	v_sub_u32_e32 v168, v228, v176
	v_cmp_gt_u32_e32 vcc, 16, v168
	v_mul_f32_e32 v107, s20, v57
	v_mul_f32_e32 v118, s21, v118
	v_add_f32_e32 v107, v107, v118
	v_cndmask_b32_e32 v107, v202, v107, vcc

; __device__ __forceinline__ int crow(int r, int h) { return (r & 3) + 8 * (r >> 2) + 4 * h; }
;     ...
;                     const int k0 = crow(r, h2), k1 = k0 + 32;
;                     int d0 = k0 - qcl + 15, d1 = k1 - qcl + 15; d0 = d0 < 0 ? 0 : (d0 > 30 ? 30 : d0); d1 = d1 < 0 ? 0 : (d1 > 30 ? 30 : d1);
;                     const float b0 = rpbL[drow + d0], b1 = rpbL[drow + d1];
;                     s0[r] = ((unsigned)(k0 - csl) < 16u) ? s0[r] * C2S + b0 * LOG2E : -1e30f;
;                     s1[r] = ((unsigned)(k1 - csl) < 16u) ? s1[r] * C2S + b1 * LOG2E : -1e30f;
	v_sub_u32_e32 v168, v230, v176
	v_cmp_gt_u32_e32 vcc, 16, v168
	v_mul_f32_e32 v108, s20, v58
	v_mul_f32_e32 v120, s21, v120
	v_add_f32_e32 v108, v108, v120
	v_cndmask_b32_e32 v108, v202, v108, vcc

; __device__ __forceinline__ int crow(int r, int h) { return (r & 3) + 8 * (r >> 2) + 4 * h; }
;     ...
;                     const int k0 = crow(r, h2), k1 = k0 + 32;
;                     int d0 = k0 - qcl + 15, d1 = k1 - qcl + 15; d0 = d0 < 0 ? 0 : (d0 > 30 ? 30 : d0); d1 = d1 < 0 ? 0 : (d1 > 30 ? 30 : d1);
;                     const float b0 = rpbL[drow + d0], b1 = rpbL[drow + d1];
;                     s0[r] = ((unsigned)(k0 - csl) < 16u) ? s0[r] * C2S + b0 * LOG2E : -1e30f;
;                     s1[r] = ((unsigned)(k1 - csl) < 16u) ? s1[r] * C2S + b1 * LOG2E : -1e30f;
	v_sub_u32_e32 v168, v232, v176
	v_cmp_gt_u32_e32 vcc, 16, v168
	v_mul_f32_e32 v109, s20, v59
	v_mul_f32_e32 v122, s21, v122
	v_add_f32_e32 v109, v109, v122
	v_cndmask_b32_e32 v109, v202, v109, vcc

; __device__ __forceinline__ int crow(int r, int h) { return (r & 3) + 8 * (r >> 2) + 4 * h; }
;     ...
;                     const int k0 = crow(r, h2), k1 = k0 + 32;
;                     int d0 = k0 - qcl + 15, d1 = k1 - qcl + 15; d0 = d0 < 0 ? 0 : (d0 > 30 ? 30 : d0); d1 = d1 < 0 ? 0 : (d1 > 30 ? 30 : d1);
;                     const float b0 = rpbL[drow + d0], b1 = rpbL[drow + d1];
;                     s0[r] = ((unsigned)(k0 - csl) < 16u) ? s0[r] * C2S + b0 * LOG2E : -1e30f;
;                     s1[r] = ((unsigned)(k1 - csl) < 16u) ? s1[r] * C2S + b1 * LOG2E : -1e30f;
	v_sub_u32_e32 v168, v234, v176
	v_cmp_gt_u32_e32 vcc, 16, v168
	v_mul_f32_e32 v110, s20, v60
	v_mul_f32_e32 v124, s21, v124
	v_add_f32_e32 v110, v110, v124
	v_cndmask_b32_e32 v110, v202, v110, vcc

; __device__ __forceinline__ int crow(int r, int h) { return (r & 3) + 8 * (r >> 2) + 4 * h; }
;     ...
;                     const int k0 = crow(r, h2), k1 = k0 + 32;
;                     int d0 = k0 - qcl + 15, d1 = k1 - qcl + 15; d0 = d0 < 0 ? 0 : (d0 > 30 ? 30 : d0); d1 = d1 < 0 ? 0 : (d1 > 30 ? 30 : d1);
;                     const float b0 = rpbL[drow + d0], b1 = rpbL[drow + d1];
;                     s0[r] = ((unsigned)(k0 - csl) < 16u) ? s0[r] * C2S + b0 * LOG2E : -1e30f;
;                     s1[r] = ((unsigned)(k1 - csl) < 16u) ? s1[r] * C2S + b1 * LOG2E : -1e30f;
	v_sub_u32_e32 v168, v236, v176
	v_cmp_gt_u32_e32 vcc, 16, v168
	v_mul_f32_e32 v111, s20, v61
	v_mul_f32_e32 v126, s21, v126
	v_add_f32_e32 v111, v111, v126
	v_cndmask_b32_e32 v111, v202, v111, vcc

; __device__ __forceinline__ int crow(int r, int h) { return (r & 3) + 8 * (r >> 2) + 4 * h; }
;     ...
;                     const int k0 = crow(r, h2), k1 = k0 + 32;
;                     int d0 = k0 - qcl + 15, d1 = k1 - qcl + 15; d0 = d0 < 0 ? 0 : (d0 > 30 ? 30 : d0); d1 = d1 < 0 ? 0 : (d1 > 30 ? 30 : d1);
;                     const float b0 = rpbL[drow + d0], b1 = rpbL[drow + d1];
;                     s0[r] = ((unsigned)(k0 - csl) < 16u) ? s0[r] * C2S + b0 * LOG2E : -1e30f;
;                     s1[r] = ((unsigned)(k1 - csl) < 16u) ? s1[r] * C2S + b1 * LOG2E : -1e30f;
	v_sub_u32_e32 v168, v238, v176
	v_cmp_gt_u32_e32 vcc, 16, v168
	v_mul_f32_e32 v112, s20, v62
	v_mul_f32_e32 v128, s21, v128
	v_add_f32_e32 v112, v112, v128
	v_cndmask_b32_e32 v112, v202, v112, vcc

; __device__ __forceinline__ int crow(int r, int h) { return (r & 3) + 8 * (r >> 2) + 4 * h; }
;     ...
;                     const int k0 = crow(r, h2), k1 = k0 + 32;
;                     int d0 = k0 - qcl + 15, d1 = k1 - qcl + 15; d0 = d0 < 0 ? 0 : (d0 > 30 ? 30 : d0); d1 = d1 < 0 ? 0 : (d1 > 30 ? 30 : d1);
;                     const float b0 = rpbL[drow + d0], b1 = rpbL[drow + d1];
;                     s0[r] = ((unsigned)(k0 - csl) < 16u) ? s0[r] * C2S + b0 * LOG2E : -1e30f;
;                     s1[r] = ((unsigned)(k1 - csl) < 16u) ? s1[r] * C2S + b1 * LOG2E : -1e30f;
	v_sub_u32_e32 v168, v240, v176
	v_cmp_gt_u32_e32 vcc, 16, v168
	v_mul_f32_e32 v113, s20, v63
	v_mul_f32_e32 v164, s21, v164
	v_add_f32_e32 v113, v113, v164
	v_cndmask_b32_e32 v113, v202, v113, vcc

; __device__ __forceinline__ int crow(int r, int h) { return (r & 3) + 8 * (r >> 2) + 4 * h; }
;     ...
;                     const int k0 = crow(r, h2), k1 = k0 + 32;
;                     int d0 = k0 - qcl + 15, d1 = k1 - qcl + 15; d0 = d0 < 0 ? 0 : (d0 > 30 ? 30 : d0); d1 = d1 < 0 ? 0 : (d1 > 30 ? 30 : d1);
;                     const float b0 = rpbL[drow + d0], b1 = rpbL[drow + d1];
	v_sub_u32_e32 v166, v211, v114
	v_med3_i32 v166, v166, -15, 15
	v_lshl_add_u32 v166, v166, 2, s4
	ds_read_b32 v115, v166 offset:44988

; __device__ __forceinline__ int crow(int r, int h) { return (r & 3) + 8 * (r >> 2) + 4 * h; }
;     ...
;                     const int k0 = crow(r, h2), k1 = k0 + 32;
;                     int d0 = k0 - qcl + 15, d1 = k1 - qcl + 15; d0 = d0 < 0 ? 0 : (d0 > 30 ? 30 : d0); d1 = d1 < 0 ? 0 : (d1 > 30 ? 30 : d1);
;                     const float b0 = rpbL[drow + d0], b1 = rpbL[drow + d1];
	v_sub_u32_e32 v166, v213, v114
	v_med3_i32 v166, v166, -15, 15
	v_lshl_add_u32 v166, v166, 2, s4
	ds_read_b32 v117, v166 offset:44988

; __device__ __forceinline__ int crow(int r, int h) { return (r & 3) + 8 * (r >> 2) + 4 * h; }
;     ...
;                     const int k0 = crow(r, h2), k1 = k0 + 32;
;                     int d0 = k0 - qcl + 15, d1 = k1 - qcl + 15; d0 = d0 < 0 ? 0 : (d0 > 30 ? 30 : d0); d1 = d1 < 0 ? 0 : (d1 > 30 ? 30 : d1);
;                     const float b0 = rpbL[drow + d0], b1 = rpbL[drow + d1];
	v_sub_u32_e32 v166, v215, v114
	v_med3_i32 v166, v166, -15, 15
	v_lshl_add_u32 v166, v166, 2, s4
	ds_read_b32 v119, v166 offset:44988

; __device__ __forceinline__ int crow(int r, int h) { return (r & 3) + 8 * (r >> 2) + 4 * h; }
;     ...
;                     const int k0 = crow(r, h2), k1 = k0 + 32;
;                     int d0 = k0 - qcl + 15, d1 = k1 - qcl + 15; d0 = d0 < 0 ? 0 : (d0 > 30 ? 30 : d0); d1 = d1 < 0 ? 0 : (d1 > 30 ? 30 : d1);
;                     const float b0 = rpbL[drow + d0], b1 = rpbL[drow + d1];
	v_sub_u32_e32 v166, v217, v114
	v_med3_i32 v166, v166, -15, 15
	v_lshl_add_u32 v166, v166, 2, s4
	ds_read_b32 v121, v166 offset:44988

; __device__ __forceinline__ int crow(int r, int h) { return (r & 3) + 8 * (r >> 2) + 4 * h; }
;     ...
;                     const int k0 = crow(r, h2), k1 = k0 + 32;
;                     int d0 = k0 - qcl + 15, d1 = k1 - qcl + 15; d0 = d0 < 0 ? 0 : (d0 > 30 ? 30 : d0); d1 = d1 < 0 ? 0 : (d1 > 30 ? 30 : d1);
;                     const float b0 = rpbL[drow + d0], b1 = rpbL[drow + d1];
	v_sub_u32_e32 v166, v219, v114
	v_med3_i32 v166, v166, -15, 15
	v_lshl_add_u32 v166, v166, 2, s4
	ds_read_b32 v123, v166 offset:44988

; __device__ __forceinline__ int crow(int r, int h) { return (r & 3) + 8 * (r >> 2) + 4 * h; }
;     ...
;                     const int k0 = crow(r, h2), k1 = k0 + 32;
;                     int d0 = k0 - qcl + 15, d1 = k1 - qcl + 15; d0 = d0 < 0 ? 0 : (d0 > 30 ? 30 : d0); d1 = d1 < 0 ? 0 : (d1 > 30 ? 30 : d1);
;                     const float b0 = rpbL[drow + d0], b1 = rpbL[drow + d1];
	v_sub_u32_e32 v166, v221, v114
	v_med3_i32 v166, v166, -15, 15
	v_lshl_add_u32 v166, v166, 2, s4
	ds_read_b32 v125, v166 offset:44988

; __device__ __forceinline__ int crow(int r, int h) { return (r & 3) + 8 * (r >> 2) + 4 * h; }
;     ...
;                     const int k0 = crow(r, h2), k1 = k0 + 32;
;                     int d0 = k0 - qcl + 15, d1 = k1 - qcl + 15; d0 = d0 < 0 ? 0 : (d0 > 30 ? 30 : d0); d1 = d1 < 0 ? 0 : (d1 > 30 ? 30 : d1);
;                     const float b0 = rpbL[drow + d0], b1 = rpbL[drow + d1];
	v_sub_u32_e32 v166, v223, v114
	v_med3_i32 v166, v166, -15, 15
	v_lshl_add_u32 v166, v166, 2, s4
	ds_read_b32 v127, v166 offset:44988

; __device__ __forceinline__ int crow(int r, int h) { return (r & 3) + 8 * (r >> 2) + 4 * h; }
;     ...
;                     const int k0 = crow(r, h2), k1 = k0 + 32;
;                     int d0 = k0 - qcl + 15, d1 = k1 - qcl + 15; d0 = d0 < 0 ? 0 : (d0 > 30 ? 30 : d0); d1 = d1 < 0 ? 0 : (d1 > 30 ? 30 : d1);
;                     const float b0 = rpbL[drow + d0], b1 = rpbL[drow + d1];
	v_sub_u32_e32 v166, v225, v114
	v_med3_i32 v166, v166, -15, 15
	v_lshl_add_u32 v166, v166, 2, s4
	ds_read_b32 v129, v166 offset:44988

; __device__ __forceinline__ int crow(int r, int h) { return (r & 3) + 8 * (r >> 2) + 4 * h; }
;     ...
;                     const int k0 = crow(r, h2), k1 = k0 + 32;
;                     int d0 = k0 - qcl + 15, d1 = k1 - qcl + 15; d0 = d0 < 0 ? 0 : (d0 > 30 ? 30 : d0); d1 = d1 < 0 ? 0 : (d1 > 30 ? 30 : d1);
;                     const float b0 = rpbL[drow + d0], b1 = rpbL[drow + d1];
	v_sub_u32_e32 v166, v227, v114
	v_med3_i32 v166, v166, -15, 15
	v_lshl_add_u32 v166, v166, 2, s4
	ds_read_b32 v165, v166 offset:44988

; __device__ __forceinline__ int crow(int r, int h) { return (r & 3) + 8 * (r >> 2) + 4 * h; }
;     ...
;                     const int k0 = crow(r, h2), k1 = k0 + 32;
;                     int d0 = k0 - qcl + 15, d1 = k1 - qcl + 15; d0 = d0 < 0 ? 0 : (d0 > 30 ? 30 : d0); d1 = d1 < 0 ? 0 : (d1 > 30 ? 30 : d1);
;                     const float b0 = rpbL[drow + d0], b1 = rpbL[drow + d1];
	v_sub_u32_e32 v166, v229, v114
	v_med3_i32 v166, v166, -15, 15
	v_lshl_add_u32 v166, v166, 2, s4
	ds_read_b32 v167, v166 offset:44988

; __device__ __forceinline__ int crow(int r, int h) { return (r & 3) + 8 * (r >> 2) + 4 * h; }
;     ...
;                     const int k0 = crow(r, h2), k1 = k0 + 32;
;                     int d0 = k0 - qcl + 15, d1 = k1 - qcl + 15; d0 = d0 < 0 ? 0 : (d0 > 30 ? 30 : d0); d1 = d1 < 0 ? 0 : (d1 > 30 ? 30 : d1);
;                     const float b0 = rpbL[drow + d0], b1 = rpbL[drow + d1];
	v_sub_u32_e32 v166, v231, v114
	v_med3_i32 v166, v166, -15, 15
	v_lshl_add_u32 v166, v166, 2, s4
	ds_read_b32 v169, v166 offset:44988

; __device__ __forceinline__ int crow(int r, int h) { return (r & 3) + 8 * (r >> 2) + 4 * h; }
;     ...
;                     const int k0 = crow(r, h2), k1 = k0 + 32;
;                     int d0 = k0 - qcl + 15, d1 = k1 - qcl + 15; d0 = d0 < 0 ? 0 : (d0 > 30 ? 30 : d0); d1 = d1 < 0 ? 0 : (d1 > 30 ? 30 : d1);
;                     const float b0 = rpbL[drow + d0], b1 = rpbL[drow + d1];
	v_sub_u32_e32 v166, v233, v114
	v_med3_i32 v166, v166, -15, 15
	v_lshl_add_u32 v166, v166, 2, s4
	ds_read_b32 v171, v166 offset:44988

; __device__ __forceinline__ int crow(int r, int h) { return (r & 3) + 8 * (r >> 2) + 4 * h; }
;     ...
;                     const int k0 = crow(r, h2), k1 = k0 + 32;
;                     int d0 = k0 - qcl + 15, d1 = k1 - qcl + 15; d0 = d0 < 0 ? 0 : (d0 > 30 ? 30 : d0); d1 = d1 < 0 ? 0 : (d1 > 30 ? 30 : d1);
;                     const float b0 = rpbL[drow + d0], b1 = rpbL[drow + d1];
	v_sub_u32_e32 v166, v235, v114
	v_med3_i32 v166, v166, -15, 15
	v_lshl_add_u32 v166, v166, 2, s4
	ds_read_b32 v173, v166 offset:44988

; __device__ __forceinline__ int crow(int r, int h) { return (r & 3) + 8 * (r >> 2) + 4 * h; }
;     ...
;                     const int k0 = crow(r, h2), k1 = k0 + 32;
;                     int d0 = k0 - qcl + 15, d1 = k1 - qcl + 15; d0 = d0 < 0 ? 0 : (d0 > 30 ? 30 : d0); d1 = d1 < 0 ? 0 : (d1 > 30 ? 30 : d1);
;                     const float b0 = rpbL[drow + d0], b1 = rpbL[drow + d1];
	v_sub_u32_e32 v166, v237, v114
	v_med3_i32 v166, v166, -15, 15
	v_lshl_add_u32 v166, v166, 2, s4
	ds_read_b32 v175, v166 offset:44988

; __device__ __forceinline__ int crow(int r, int h) { return (r & 3) + 8 * (r >> 2) + 4 * h; }
;     ...
;                     const int k0 = crow(r, h2), k1 = k0 + 32;
;                     int d0 = k0 - qcl + 15, d1 = k1 - qcl + 15; d0 = d0 < 0 ? 0 : (d0 > 30 ? 30 : d0); d1 = d1 < 0 ? 0 : (d1 > 30 ? 30 : d1);
;                     const float b0 = rpbL[drow + d0], b1 = rpbL[drow + d1];
	v_sub_u32_e32 v166, v239, v114
	v_med3_i32 v166, v166, -15, 15
	v_lshl_add_u32 v166, v166, 2, s4
	ds_read_b32 v179, v166 offset:44988

; __device__ __forceinline__ int crow(int r, int h) { return (r & 3) + 8 * (r >> 2) + 4 * h; }
;     ...
;                     const int k0 = crow(r, h2), k1 = k0 + 32;
;                     int d0 = k0 - qcl + 15, d1 = k1 - qcl + 15; d0 = d0 < 0 ? 0 : (d0 > 30 ? 30 : d0); d1 = d1 < 0 ? 0 : (d1 > 30 ? 30 : d1);
;                     const float b0 = rpbL[drow + d0], b1 = rpbL[drow + d1];
	v_sub_u32_e32 v166, v241, v114
	v_med3_i32 v166, v166, -15, 15
	v_lshl_add_u32 v166, v166, 2, s4
	ds_read_b32 v177, v166 offset:44988

; __device__ __forceinline__ int crow(int r, int h) { return (r & 3) + 8 * (r >> 2) + 4 * h; }
;     ...
;                 for (int r = 0; r < 16; ++r) {
;                     const int k0 = crow(r, h2), k1 = k0 + 32;
;                     int d0 = k0 - qcl + 15, d1 = k1 - qcl + 15; d0 = d0 < 0 ? 0 : (d0 > 30 ? 30 : d0); d1 = d1 < 0 ? 0 : (d1 > 30 ? 30 : d1);
;                     const float b0 = rpbL[drow + d0], b1 = rpbL[drow + d1];
;                     s0[r] = ((unsigned)(k0 - csl) < 16u) ? s0[r] * C2S + b0 * LOG2E : -1e30f;
;                     s1[r] = ((unsigned)(k1 - csl) < 16u) ? s1[r] * C2S + b1 * LOG2E : -1e30f;
;                 }
	v_sub_u32_e32 v114, v211, v176
	v_cmp_gt_u32_e32 vcc, 16, v114
	v_mov_b32_e32 v114, v32
	s_waitcnt lgkmcnt(14)
	v_pk_mul_f32 v[114:115], v[114:115], s[20:21]
	v_mov_b32_e32 v116, v33
	v_add_f32_e32 v114, v114, v115
	v_sub_u32_e32 v115, v213, v176
	v_pk_mul_f32 v[116:117], v[116:117], s[20:21]
	v_cndmask_b32_e32 v114, v202, v114, vcc
	v_cmp_gt_u32_e32 vcc, 16, v115
	v_add_f32_e32 v115, v116, v117
	v_sub_u32_e32 v116, v215, v176
	v_mov_b32_e32 v118, v34
	v_cndmask_b32_e32 v115, v202, v115, vcc
	v_cmp_gt_u32_e32 vcc, 16, v116
	s_waitcnt lgkmcnt(13)
	v_pk_mul_f32 v[116:117], v[118:119], s[20:21]
	v_mov_b32_e32 v120, v35
	v_add_f32_e32 v116, v116, v117
	v_sub_u32_e32 v117, v217, v176
	s_waitcnt lgkmcnt(12)
	v_pk_mul_f32 v[118:119], v[120:121], s[20:21]
	v_cndmask_b32_e32 v116, v202, v116, vcc
	v_cmp_gt_u32_e32 vcc, 16, v117
	v_add_f32_e32 v117, v118, v119
	v_sub_u32_e32 v118, v219, v176
	v_mov_b32_e32 v122, v36
	v_cndmask_b32_e32 v117, v202, v117, vcc
	v_cmp_gt_u32_e32 vcc, 16, v118
	s_waitcnt lgkmcnt(11)
	v_pk_mul_f32 v[118:119], v[122:123], s[20:21]
	v_mov_b32_e32 v124, v37
	v_add_f32_e32 v118, v118, v119
	v_sub_u32_e32 v119, v221, v176
	s_waitcnt lgkmcnt(10)
	v_pk_mul_f32 v[120:121], v[124:125], s[20:21]
	v_cndmask_b32_e32 v118, v202, v118, vcc
	v_cmp_gt_u32_e32 vcc, 16, v119
	v_add_f32_e32 v119, v120, v121
	v_sub_u32_e32 v120, v223, v176
	v_mov_b32_e32 v126, v38
	v_cndmask_b32_e32 v119, v202, v119, vcc
	v_cmp_gt_u32_e32 vcc, 16, v120
	s_waitcnt lgkmcnt(9)
	v_pk_mul_f32 v[120:121], v[126:127], s[20:21]
	v_mov_b32_e32 v128, v39
	v_add_f32_e32 v120, v120, v121
	v_sub_u32_e32 v121, v225, v176
	s_waitcnt lgkmcnt(8)
	v_pk_mul_f32 v[122:123], v[128:129], s[20:21]
	v_cndmask_b32_e32 v120, v202, v120, vcc
	v_cmp_gt_u32_e32 vcc, 16, v121
	v_add_f32_e32 v121, v122, v123
	v_sub_u32_e32 v122, v227, v176
	v_mov_b32_e32 v164, v40
	v_cndmask_b32_e32 v121, v202, v121, vcc
	v_cmp_gt_u32_e32 vcc, 16, v122
	s_waitcnt lgkmcnt(7)
	v_pk_mul_f32 v[122:123], v[164:165], s[20:21]
	v_mov_b32_e32 v166, v41
	v_add_f32_e32 v122, v122, v123
	v_sub_u32_e32 v123, v229, v176
	s_waitcnt lgkmcnt(6)
	v_pk_mul_f32 v[124:125], v[166:167], s[20:21]
	v_cndmask_b32_e32 v122, v202, v122, vcc
	v_cmp_gt_u32_e32 vcc, 16, v123
	v_add_f32_e32 v123, v124, v125
	v_sub_u32_e32 v124, v231, v176
	v_mov_b32_e32 v168, v42
	v_cndmask_b32_e32 v123, v202, v123, vcc
	v_cmp_gt_u32_e32 vcc, 16, v124
	s_waitcnt lgkmcnt(5)
	v_pk_mul_f32 v[124:125], v[168:169], s[20:21]
	v_mov_b32_e32 v170, v43
	v_add_f32_e32 v124, v124, v125
	v_sub_u32_e32 v125, v233, v176
	s_waitcnt lgkmcnt(4)
	v_pk_mul_f32 v[126:127], v[170:171], s[20:21]
	v_cndmask_b32_e32 v124, v202, v124, vcc
	v_cmp_gt_u32_e32 vcc, 16, v125
	v_add_f32_e32 v125, v126, v127
	v_sub_u32_e32 v126, v235, v176
	v_mov_b32_e32 v172, v44
	v_cndmask_b32_e32 v125, v202, v125, vcc
	v_cmp_gt_u32_e32 vcc, 16, v126
	s_waitcnt lgkmcnt(3)
	v_pk_mul_f32 v[126:127], v[172:173], s[20:21]
	v_mov_b32_e32 v174, v45
	v_add_f32_e32 v126, v126, v127
	v_sub_u32_e32 v127, v237, v176
	s_waitcnt lgkmcnt(2)
	v_pk_mul_f32 v[128:129], v[174:175], s[20:21]
	v_cndmask_b32_e32 v126, v202, v126, vcc
	v_cmp_gt_u32_e32 vcc, 16, v127
	v_add_f32_e32 v127, v128, v129
	v_sub_u32_e32 v128, v239, v176
	v_mov_b32_e32 v178, v46
	v_cndmask_b32_e32 v127, v202, v127, vcc
	v_cmp_gt_u32_e32 vcc, 16, v128
	s_waitcnt lgkmcnt(1)
	v_pk_mul_f32 v[128:129], v[178:179], s[20:21]
	s_mov_b64 s[48:49], -1
	v_add_f32_e32 v128, v128, v129
	v_sub_u32_e32 v129, v241, v176
	v_mov_b32_e32 v176, v47
	s_waitcnt lgkmcnt(0)
	v_pk_mul_f32 v[164:165], v[176:177], s[20:21]
	v_cndmask_b32_e32 v128, v202, v128, vcc
	v_cmp_gt_u32_e32 vcc, 16, v129
	v_add_f32_e32 v129, v164, v165
	s_nop 0
	v_cndmask_b32_e32 v129, v202, v129, vcc
